# WO epilogue: second-half x loads issued together with the first-half loads (one round trip per row group instead of two)
# baseline (speedup 1.0000x reference)
.LBB0_1066:
	v_lshl_add_u64 v[178:179], s[80:81], 0, v[182:183]
	v_lshl_add_u64 v[182:183], v[180:181], 0, v[174:175]
	global_load_dwordx4 v[204:207], v[182:183], off offset:528
	global_load_dwordx4 v[200:203], v[182:183], off offset:512
	global_load_dwordx4 v[190:193], v[182:183], off offset:16
	global_load_dwordx4 v[196:199], v[182:183], off
	v_lshl_add_u64 v[182:183], v[178:179], 0, v[174:175]
	v_ashrrev_i32_e32 v177, 31, v176
	s_lshl_b32 s28, s28, 2
	s_ashr_i32 s29, s28, 31
	s_waitcnt vmcnt(0)
	v_pk_fma_f32 v[154:155], v[154:155], v[58:59], v[192:193]
	v_pk_fma_f32 v[158:159], v[158:159], v[54:55], v[198:199]
	v_pk_fma_f32 v[156:157], v[156:157], v[52:53], v[196:197]
	v_pk_fma_f32 v[152:153], v[152:153], v[56:57], v[190:191]
	global_store_dwordx4 v[182:183], v[156:159], off
	global_store_dwordx4 v[182:183], v[152:155], off offset:16
	v_mul_f32_e32 v182, v157, v157
	v_mul_f32_e32 v183, v159, v159
	v_fmac_f32_e32 v182, v156, v156
	v_fmac_f32_e32 v183, v158, v158
	v_add_f32_e32 v182, v182, v183
	v_mul_f32_e32 v183, v153, v153
	v_mul_f32_e32 v156, v48, v156
	v_mul_f32_e32 v157, v49, v157
	v_fmac_f32_e32 v183, v152, v152
	v_cvt_pk_bf16_f32 v156, v156, v157
	v_mul_f32_e32 v157, v50, v158
	v_mul_f32_e32 v158, v51, v159
	v_mul_f32_e32 v152, v60, v152
	v_mul_f32_e32 v153, v61, v153
	v_cvt_pk_bf16_f32 v157, v157, v158
	v_cvt_pk_bf16_f32 v158, v152, v153
	v_mul_f32_e32 v152, v62, v154
	v_mul_f32_e32 v153, v63, v155
	v_add_f32_e32 v182, v182, v183
	v_mul_f32_e32 v183, v155, v155
	v_cvt_pk_bf16_f32 v159, v152, v153
	v_lshlrev_b64 v[152:153], 11, v[176:177]
	v_fmac_f32_e32 v183, v154, v154
	v_lshl_add_u64 v[154:155], s[16:17], 0, v[152:153]
	v_lshl_add_u64 v[152:153], v[172:173], 1, v[154:155]
	global_store_dwordx4 v[152:153], v[156:159], off
	v_lshlrev_b64 v[152:153], 2, v[172:173]
	v_lshl_add_u64 v[180:181], v[180:181], 0, v[152:153]
	v_add_f32_e32 v184, v183, v182
	v_mov_b32_e32 v156, v204
	v_mov_b32_e32 v157, v205
	v_mov_b32_e32 v158, v206
	v_mov_b32_e32 v159, v207
	v_mov_b32_e32 v180, v200
	v_mov_b32_e32 v181, v201
	v_mov_b32_e32 v182, v202
	v_mov_b32_e32 v183, v203
	s_waitcnt vmcnt(3)
	v_pk_fma_f32 v[144:145], v[144:145], v[36:37], v[156:157]
	s_waitcnt vmcnt(3)
	v_pk_fma_f32 v[150:151], v[150:151], v[34:35], v[182:183]
	v_pk_fma_f32 v[148:149], v[148:149], v[32:33], v[180:181]
	v_lshl_add_u64 v[156:157], v[178:179], 0, v[152:153]
	v_pk_fma_f32 v[146:147], v[146:147], v[38:39], v[158:159]
	global_store_dwordx4 v[156:157], v[148:151], off offset:512
	global_store_dwordx4 v[156:157], v[144:147], off offset:528
	v_mul_f32_e32 v156, v149, v149
	v_mul_f32_e32 v157, v151, v151
	v_fmac_f32_e32 v156, v148, v148
	v_fmac_f32_e32 v157, v150, v150
	v_add_f32_e32 v156, v156, v157
	v_mul_f32_e32 v157, v145, v145
	v_mul_f32_e32 v148, v24, v148
	v_mul_f32_e32 v149, v25, v149
	v_fmac_f32_e32 v157, v144, v144
	v_cvt_pk_bf16_f32 v148, v148, v149
	v_mul_f32_e32 v149, v26, v150
	v_mul_f32_e32 v150, v27, v151
	v_mul_f32_e32 v144, v28, v144
	v_mul_f32_e32 v145, v29, v145
	v_cvt_pk_bf16_f32 v149, v149, v150
	v_cvt_pk_bf16_f32 v150, v144, v145
	v_mul_f32_e32 v144, v30, v146
	v_mul_f32_e32 v145, v31, v147
	v_cvt_pk_bf16_f32 v151, v144, v145
	v_lshl_add_u64 v[144:145], v[172:173], 1, v[154:155]
	global_store_dwordx4 v[144:145], v[148:151], off offset:256
	v_and_b32_e32 v145, 64, v221
	v_add_f32_e32 v156, v156, v157
	v_mul_f32_e32 v157, v147, v147
	v_xor_b32_e32 v144, 16, v221
	v_add_u32_e32 v145, 64, v145
	v_fmac_f32_e32 v157, v146, v146
	v_cmp_lt_i32_e32 vcc, v144, v145
	v_add_f32_e32 v156, v157, v156
	v_add_f32_e32 v156, v184, v156
	v_cndmask_b32_e32 v144, v221, v144, vcc
	v_lshlrev_b32_e32 v154, 2, v144
	ds_bpermute_b32 v144, v154, v156
	v_xor_b32_e32 v146, 32, v221
	v_cmp_lt_i32_e32 vcc, v146, v145
	s_waitcnt lgkmcnt(0)
	v_add_f32_e32 v144, v156, v144
	v_cndmask_b32_e32 v145, v221, v146, vcc
	v_lshlrev_b32_e32 v155, 2, v145
	ds_bpermute_b32 v145, v155, v144
	s_and_saveexec_b64 s[30:31], s[72:73]
	s_cbranch_execz .LBB0_1068
	v_lshlrev_b64 v[146:147], 6, v[176:177]
	v_lshl_add_u64 v[146:147], s[18:19], 0, v[146:147]
	v_lshl_add_u64 v[146:147], s[28:29], 2, v[146:147]
	s_lshl_b32 s96, s46, 2
	v_lshl_add_u64 v[146:147], v[146:147], 0, s[96:97]
	s_waitcnt lgkmcnt(0)
	v_add_f32_e32 v144, v144, v145
	global_store_dword v[146:147], v144, off

.LBB0_1078:
	v_lshl_add_u64 v[146:147], s[80:81], 0, v[150:151]
	v_lshl_add_u64 v[150:151], v[148:149], 0, v[174:175]
	global_load_dwordx4 v[204:207], v[150:151], off offset:528
	global_load_dwordx4 v[200:203], v[150:151], off offset:512
	global_load_dwordx4 v[156:159], v[150:151], off offset:16
	global_load_dwordx4 v[178:181], v[150:151], off
	v_lshl_add_u64 v[150:151], v[146:147], 0, v[174:175]
	v_ashrrev_i32_e32 v145, 31, v144
	s_waitcnt vmcnt(1)
	v_pk_fma_f32 v[138:139], v[138:139], v[58:59], v[158:159]
	s_waitcnt vmcnt(0)
	v_pk_fma_f32 v[142:143], v[142:143], v[54:55], v[180:181]
	v_pk_fma_f32 v[140:141], v[140:141], v[52:53], v[178:179]
	v_pk_fma_f32 v[136:137], v[136:137], v[56:57], v[156:157]
	global_store_dwordx4 v[150:151], v[140:143], off
	global_store_dwordx4 v[150:151], v[136:139], off offset:16
	v_mul_f32_e32 v150, v141, v141
	v_mul_f32_e32 v151, v143, v143
	v_fmac_f32_e32 v150, v140, v140
	v_fmac_f32_e32 v151, v142, v142
	v_add_f32_e32 v150, v150, v151
	v_mul_f32_e32 v151, v137, v137
	v_mul_f32_e32 v140, v48, v140
	v_mul_f32_e32 v141, v49, v141
	v_fmac_f32_e32 v151, v136, v136
	v_cvt_pk_bf16_f32 v140, v140, v141
	v_mul_f32_e32 v141, v50, v142
	v_mul_f32_e32 v142, v51, v143
	v_mul_f32_e32 v136, v60, v136
	v_mul_f32_e32 v137, v61, v137
	v_cvt_pk_bf16_f32 v141, v141, v142
	v_cvt_pk_bf16_f32 v142, v136, v137
	v_mul_f32_e32 v136, v62, v138
	v_mul_f32_e32 v137, v63, v139
	v_cvt_pk_bf16_f32 v143, v136, v137
	v_lshlrev_b64 v[136:137], 11, v[144:145]
	v_add_f32_e32 v150, v150, v151
	v_mul_f32_e32 v151, v139, v139
	v_lshl_add_u64 v[136:137], s[16:17], 0, v[136:137]
	v_fmac_f32_e32 v151, v138, v138
	v_lshl_add_u64 v[138:139], v[172:173], 1, v[136:137]
	global_store_dwordx4 v[138:139], v[140:143], off
	v_add_f32_e32 v156, v151, v150
	s_nop 0
	v_lshl_add_u64 v[142:143], v[148:149], 0, v[152:153]
	v_mov_b32_e32 v138, v204
	v_mov_b32_e32 v139, v205
	v_mov_b32_e32 v140, v206
	v_mov_b32_e32 v141, v207
	v_mov_b32_e32 v148, v200
	v_mov_b32_e32 v149, v201
	v_mov_b32_e32 v150, v202
	v_mov_b32_e32 v151, v203
	s_waitcnt vmcnt(3)
	v_pk_fma_f32 v[128:129], v[128:129], v[36:37], v[138:139]
	s_waitcnt vmcnt(3)
	v_pk_fma_f32 v[134:135], v[134:135], v[34:35], v[150:151]
	v_pk_fma_f32 v[132:133], v[132:133], v[32:33], v[148:149]
	v_lshl_add_u64 v[138:139], v[146:147], 0, v[152:153]
	v_pk_fma_f32 v[130:131], v[130:131], v[38:39], v[140:141]
	global_store_dwordx4 v[138:139], v[132:135], off offset:512
	global_store_dwordx4 v[138:139], v[128:131], off offset:528
	v_mul_f32_e32 v138, v133, v133
	v_mul_f32_e32 v139, v135, v135
	v_fmac_f32_e32 v138, v132, v132
	v_fmac_f32_e32 v139, v134, v134
	v_add_f32_e32 v138, v138, v139
	v_mul_f32_e32 v139, v129, v129
	v_fmac_f32_e32 v139, v128, v128
	v_add_f32_e32 v138, v138, v139
	v_mul_f32_e32 v139, v131, v131
	v_mul_f32_e32 v132, v24, v132
	v_mul_f32_e32 v133, v25, v133
	v_fmac_f32_e32 v139, v130, v130
	v_cvt_pk_bf16_f32 v132, v132, v133
	v_mul_f32_e32 v133, v26, v134
	v_mul_f32_e32 v134, v27, v135
	v_mul_f32_e32 v128, v28, v128
	v_mul_f32_e32 v129, v29, v129
	v_add_f32_e32 v138, v139, v138
	v_cvt_pk_bf16_f32 v133, v133, v134
	v_cvt_pk_bf16_f32 v134, v128, v129
	v_mul_f32_e32 v128, v30, v130
	v_mul_f32_e32 v129, v31, v131
	v_add_f32_e32 v138, v156, v138
	v_cvt_pk_bf16_f32 v135, v128, v129
	v_lshl_add_u64 v[128:129], v[172:173], 1, v[136:137]
	global_store_dwordx4 v[128:129], v[132:135], off offset:256
	ds_bpermute_b32 v128, v154, v138
	s_waitcnt lgkmcnt(0)
	v_add_f32_e32 v128, v138, v128
	ds_bpermute_b32 v129, v155, v128
	s_and_saveexec_b64 s[30:31], s[72:73]
	s_cbranch_execz .LBB0_1080
	v_lshlrev_b64 v[130:131], 6, v[144:145]
	v_lshl_add_u64 v[130:131], s[18:19], 0, v[130:131]
	v_lshl_add_u64 v[130:131], s[28:29], 2, v[130:131]
	s_lshl_b32 s96, s46, 2
	v_lshl_add_u64 v[130:131], v[130:131], 0, s[96:97]
	s_waitcnt lgkmcnt(0)
	v_add_f32_e32 v128, v128, v129
	global_store_dword v[130:131], v128, off

.LBB0_1090:
	v_lshl_add_u64 v[138:139], v[132:133], 0, v[174:175]
	v_lshl_add_u64 v[130:131], s[80:81], 0, v[134:135]
	global_load_dwordx4 v[204:207], v[138:139], off offset:528
	global_load_dwordx4 v[200:203], v[138:139], off offset:512
	global_load_dwordx4 v[134:137], v[138:139], off offset:16
	s_nop 0
	global_load_dwordx4 v[138:141], v[138:139], off
	v_ashrrev_i32_e32 v129, 31, v128
	s_waitcnt vmcnt(1)
	v_pk_fma_f32 v[120:121], v[120:121], v[56:57], v[134:135]
	s_waitcnt vmcnt(0)
	v_pk_fma_f32 v[126:127], v[126:127], v[54:55], v[140:141]
	v_pk_fma_f32 v[124:125], v[124:125], v[52:53], v[138:139]
	v_lshl_add_u64 v[134:135], v[130:131], 0, v[174:175]
	v_pk_fma_f32 v[122:123], v[122:123], v[58:59], v[136:137]
	global_store_dwordx4 v[134:135], v[124:127], off
	global_store_dwordx4 v[134:135], v[120:123], off offset:16
	v_mul_f32_e32 v134, v125, v125
	v_mul_f32_e32 v135, v127, v127
	v_fmac_f32_e32 v134, v124, v124
	v_fmac_f32_e32 v135, v126, v126
	v_add_f32_e32 v134, v134, v135
	v_mul_f32_e32 v135, v121, v121
	v_mul_f32_e32 v124, v48, v124
	v_mul_f32_e32 v125, v49, v125
	v_fmac_f32_e32 v135, v120, v120
	v_cvt_pk_bf16_f32 v124, v124, v125
	v_mul_f32_e32 v125, v50, v126
	v_mul_f32_e32 v126, v51, v127
	v_mul_f32_e32 v120, v60, v120
	v_mul_f32_e32 v121, v61, v121
	v_cvt_pk_bf16_f32 v125, v125, v126
	v_cvt_pk_bf16_f32 v126, v120, v121
	v_mul_f32_e32 v120, v62, v122
	v_mul_f32_e32 v121, v63, v123
	v_cvt_pk_bf16_f32 v127, v120, v121
	v_lshlrev_b64 v[120:121], 11, v[128:129]
	v_add_f32_e32 v134, v134, v135
	v_mul_f32_e32 v135, v123, v123
	v_lshl_add_u64 v[120:121], s[16:17], 0, v[120:121]
	v_fmac_f32_e32 v135, v122, v122
	v_lshl_add_u64 v[122:123], v[172:173], 1, v[120:121]
	global_store_dwordx4 v[122:123], v[124:127], off
	v_add_f32_e32 v136, v135, v134
	s_nop 0
	v_lshl_add_u64 v[126:127], v[132:133], 0, v[152:153]
	v_mov_b32_e32 v122, v204
	v_mov_b32_e32 v123, v205
	v_mov_b32_e32 v124, v206
	v_mov_b32_e32 v125, v207
	v_mov_b32_e32 v132, v200
	v_mov_b32_e32 v133, v201
	v_mov_b32_e32 v134, v202
	v_mov_b32_e32 v135, v203
	s_waitcnt vmcnt(3)
	v_pk_fma_f32 v[112:113], v[112:113], v[36:37], v[122:123]
	s_waitcnt vmcnt(3)
	v_pk_fma_f32 v[118:119], v[118:119], v[34:35], v[134:135]
	v_pk_fma_f32 v[116:117], v[116:117], v[32:33], v[132:133]
	v_lshl_add_u64 v[122:123], v[130:131], 0, v[152:153]
	v_pk_fma_f32 v[114:115], v[114:115], v[38:39], v[124:125]
	global_store_dwordx4 v[122:123], v[116:119], off offset:512
	global_store_dwordx4 v[122:123], v[112:115], off offset:528
	v_mul_f32_e32 v122, v117, v117
	v_mul_f32_e32 v123, v119, v119
	v_fmac_f32_e32 v122, v116, v116
	v_fmac_f32_e32 v123, v118, v118
	v_add_f32_e32 v122, v122, v123
	v_mul_f32_e32 v123, v113, v113
	v_fmac_f32_e32 v123, v112, v112
	v_add_f32_e32 v122, v122, v123
	v_mul_f32_e32 v123, v115, v115
	v_mul_f32_e32 v116, v24, v116
	v_mul_f32_e32 v117, v25, v117
	v_fmac_f32_e32 v123, v114, v114
	v_cvt_pk_bf16_f32 v116, v116, v117
	v_mul_f32_e32 v117, v26, v118
	v_mul_f32_e32 v118, v27, v119
	v_mul_f32_e32 v112, v28, v112
	v_mul_f32_e32 v113, v29, v113
	v_add_f32_e32 v122, v123, v122
	v_cvt_pk_bf16_f32 v117, v117, v118
	v_cvt_pk_bf16_f32 v118, v112, v113
	v_mul_f32_e32 v112, v30, v114
	v_mul_f32_e32 v113, v31, v115
	v_add_f32_e32 v122, v136, v122
	v_cvt_pk_bf16_f32 v119, v112, v113
	v_lshl_add_u64 v[112:113], v[172:173], 1, v[120:121]
	global_store_dwordx4 v[112:113], v[116:119], off offset:256
	ds_bpermute_b32 v112, v154, v122
	s_waitcnt lgkmcnt(0)
	v_add_f32_e32 v112, v122, v112
	ds_bpermute_b32 v113, v155, v112
	s_and_saveexec_b64 s[30:31], s[72:73]
	s_cbranch_execz .LBB0_1092
	v_lshlrev_b64 v[114:115], 6, v[128:129]
	v_lshl_add_u64 v[114:115], s[18:19], 0, v[114:115]
	v_lshl_add_u64 v[114:115], s[28:29], 2, v[114:115]
	s_lshl_b32 s96, s46, 2
	v_lshl_add_u64 v[114:115], v[114:115], 0, s[96:97]
	s_waitcnt lgkmcnt(0)
	v_add_f32_e32 v112, v112, v113
	global_store_dword v[114:115], v112, off

.LBB0_1102:
	v_lshl_add_u64 v[122:123], v[116:117], 0, v[174:175]
	v_lshl_add_u64 v[114:115], s[80:81], 0, v[118:119]
	global_load_dwordx4 v[204:207], v[122:123], off offset:528
	global_load_dwordx4 v[200:203], v[122:123], off offset:512
	global_load_dwordx4 v[118:121], v[122:123], off offset:16
	s_nop 0
	global_load_dwordx4 v[122:125], v[122:123], off
	v_ashrrev_i32_e32 v113, 31, v112
	s_waitcnt vmcnt(1)
	v_pk_fma_f32 v[104:105], v[104:105], v[56:57], v[118:119]
	s_waitcnt vmcnt(0)
	v_pk_fma_f32 v[110:111], v[110:111], v[54:55], v[124:125]
	v_pk_fma_f32 v[108:109], v[108:109], v[52:53], v[122:123]
	v_lshl_add_u64 v[118:119], v[114:115], 0, v[174:175]
	v_pk_fma_f32 v[106:107], v[106:107], v[58:59], v[120:121]
	global_store_dwordx4 v[118:119], v[108:111], off
	global_store_dwordx4 v[118:119], v[104:107], off offset:16
	v_mul_f32_e32 v118, v109, v109
	v_mul_f32_e32 v119, v111, v111
	v_fmac_f32_e32 v118, v108, v108
	v_fmac_f32_e32 v119, v110, v110
	v_add_f32_e32 v118, v118, v119
	v_mul_f32_e32 v119, v105, v105
	v_mul_f32_e32 v108, v48, v108
	v_mul_f32_e32 v109, v49, v109
	v_fmac_f32_e32 v119, v104, v104
	v_cvt_pk_bf16_f32 v108, v108, v109
	v_mul_f32_e32 v109, v50, v110
	v_mul_f32_e32 v110, v51, v111
	v_mul_f32_e32 v104, v60, v104
	v_mul_f32_e32 v105, v61, v105
	v_cvt_pk_bf16_f32 v109, v109, v110
	v_cvt_pk_bf16_f32 v110, v104, v105
	v_mul_f32_e32 v104, v62, v106
	v_mul_f32_e32 v105, v63, v107
	v_cvt_pk_bf16_f32 v111, v104, v105
	v_lshlrev_b64 v[104:105], 11, v[112:113]
	v_add_f32_e32 v118, v118, v119
	v_mul_f32_e32 v119, v107, v107
	v_lshl_add_u64 v[104:105], s[16:17], 0, v[104:105]
	v_fmac_f32_e32 v119, v106, v106
	v_lshl_add_u64 v[106:107], v[172:173], 1, v[104:105]
	global_store_dwordx4 v[106:107], v[108:111], off
	v_add_f32_e32 v120, v119, v118
	s_nop 0
	v_lshl_add_u64 v[110:111], v[116:117], 0, v[152:153]
	v_mov_b32_e32 v106, v204
	v_mov_b32_e32 v107, v205
	v_mov_b32_e32 v108, v206
	v_mov_b32_e32 v109, v207
	v_mov_b32_e32 v116, v200
	v_mov_b32_e32 v117, v201
	v_mov_b32_e32 v118, v202
	v_mov_b32_e32 v119, v203
	s_waitcnt vmcnt(3)
	v_pk_fma_f32 v[96:97], v[96:97], v[36:37], v[106:107]
	s_waitcnt vmcnt(3)
	v_pk_fma_f32 v[102:103], v[102:103], v[34:35], v[118:119]
	v_pk_fma_f32 v[100:101], v[100:101], v[32:33], v[116:117]
	v_lshl_add_u64 v[106:107], v[114:115], 0, v[152:153]
	v_pk_fma_f32 v[98:99], v[98:99], v[38:39], v[108:109]
	global_store_dwordx4 v[106:107], v[100:103], off offset:512
	global_store_dwordx4 v[106:107], v[96:99], off offset:528
	v_mul_f32_e32 v106, v101, v101
	v_mul_f32_e32 v107, v103, v103
	v_fmac_f32_e32 v106, v100, v100
	v_fmac_f32_e32 v107, v102, v102
	v_add_f32_e32 v106, v106, v107
	v_mul_f32_e32 v107, v97, v97
	v_fmac_f32_e32 v107, v96, v96
	v_add_f32_e32 v106, v106, v107
	v_mul_f32_e32 v107, v99, v99
	v_mul_f32_e32 v100, v24, v100
	v_mul_f32_e32 v101, v25, v101
	v_fmac_f32_e32 v107, v98, v98
	v_cvt_pk_bf16_f32 v100, v100, v101
	v_mul_f32_e32 v101, v26, v102
	v_mul_f32_e32 v102, v27, v103
	v_mul_f32_e32 v96, v28, v96
	v_mul_f32_e32 v97, v29, v97
	v_add_f32_e32 v106, v107, v106
	v_cvt_pk_bf16_f32 v101, v101, v102
	v_cvt_pk_bf16_f32 v102, v96, v97
	v_mul_f32_e32 v96, v30, v98
	v_mul_f32_e32 v97, v31, v99
	v_add_f32_e32 v106, v120, v106
	v_cvt_pk_bf16_f32 v103, v96, v97
	v_lshl_add_u64 v[96:97], v[172:173], 1, v[104:105]
	global_store_dwordx4 v[96:97], v[100:103], off offset:256
	ds_bpermute_b32 v96, v154, v106
	s_waitcnt lgkmcnt(0)
	v_add_f32_e32 v96, v106, v96
	ds_bpermute_b32 v97, v155, v96
	s_and_saveexec_b64 s[30:31], s[72:73]
	s_cbranch_execz .LBB0_1104
	v_lshlrev_b64 v[98:99], 6, v[112:113]
	v_lshl_add_u64 v[98:99], s[18:19], 0, v[98:99]
	v_lshl_add_u64 v[98:99], s[28:29], 2, v[98:99]
	s_lshl_b32 s96, s46, 2
	v_lshl_add_u64 v[98:99], v[98:99], 0, s[96:97]
	s_waitcnt lgkmcnt(0)
	v_add_f32_e32 v96, v96, v97
	global_store_dword v[98:99], v96, off

.LBB0_1114:
	v_lshl_add_u64 v[106:107], v[100:101], 0, v[174:175]
	v_lshl_add_u64 v[98:99], s[80:81], 0, v[102:103]
	global_load_dwordx4 v[204:207], v[106:107], off offset:528
	global_load_dwordx4 v[200:203], v[106:107], off offset:512
	global_load_dwordx4 v[102:105], v[106:107], off offset:16
	s_nop 0
	global_load_dwordx4 v[106:109], v[106:107], off
	v_ashrrev_i32_e32 v97, 31, v96
	s_waitcnt vmcnt(1)
	v_pk_fma_f32 v[88:89], v[88:89], v[56:57], v[102:103]
	s_waitcnt vmcnt(0)
	v_pk_fma_f32 v[94:95], v[94:95], v[54:55], v[108:109]
	v_pk_fma_f32 v[92:93], v[92:93], v[52:53], v[106:107]
	v_lshl_add_u64 v[102:103], v[98:99], 0, v[174:175]
	v_pk_fma_f32 v[90:91], v[90:91], v[58:59], v[104:105]
	global_store_dwordx4 v[102:103], v[92:95], off
	global_store_dwordx4 v[102:103], v[88:91], off offset:16
	v_mul_f32_e32 v102, v93, v93
	v_mul_f32_e32 v103, v95, v95
	v_fmac_f32_e32 v102, v92, v92
	v_fmac_f32_e32 v103, v94, v94
	v_add_f32_e32 v102, v102, v103
	v_mul_f32_e32 v103, v89, v89
	v_mul_f32_e32 v92, v48, v92
	v_mul_f32_e32 v93, v49, v93
	v_fmac_f32_e32 v103, v88, v88
	v_cvt_pk_bf16_f32 v92, v92, v93
	v_mul_f32_e32 v93, v50, v94
	v_mul_f32_e32 v94, v51, v95
	v_mul_f32_e32 v88, v60, v88
	v_mul_f32_e32 v89, v61, v89
	v_cvt_pk_bf16_f32 v93, v93, v94
	v_cvt_pk_bf16_f32 v94, v88, v89
	v_mul_f32_e32 v88, v62, v90
	v_mul_f32_e32 v89, v63, v91
	v_cvt_pk_bf16_f32 v95, v88, v89
	v_lshlrev_b64 v[88:89], 11, v[96:97]
	v_add_f32_e32 v102, v102, v103
	v_mul_f32_e32 v103, v91, v91
	v_lshl_add_u64 v[88:89], s[16:17], 0, v[88:89]
	v_fmac_f32_e32 v103, v90, v90
	v_lshl_add_u64 v[90:91], v[172:173], 1, v[88:89]
	global_store_dwordx4 v[90:91], v[92:95], off
	v_add_f32_e32 v104, v103, v102
	s_nop 0
	v_lshl_add_u64 v[94:95], v[100:101], 0, v[152:153]
	v_mov_b32_e32 v90, v204
	v_mov_b32_e32 v91, v205
	v_mov_b32_e32 v92, v206
	v_mov_b32_e32 v93, v207
	v_mov_b32_e32 v100, v200
	v_mov_b32_e32 v101, v201
	v_mov_b32_e32 v102, v202
	v_mov_b32_e32 v103, v203
	s_waitcnt vmcnt(3)
	v_pk_fma_f32 v[80:81], v[80:81], v[36:37], v[90:91]
	s_waitcnt vmcnt(3)
	v_pk_fma_f32 v[86:87], v[86:87], v[34:35], v[102:103]
	v_pk_fma_f32 v[84:85], v[84:85], v[32:33], v[100:101]
	v_lshl_add_u64 v[90:91], v[98:99], 0, v[152:153]
	v_pk_fma_f32 v[82:83], v[82:83], v[38:39], v[92:93]
	global_store_dwordx4 v[90:91], v[84:87], off offset:512
	global_store_dwordx4 v[90:91], v[80:83], off offset:528
	v_mul_f32_e32 v90, v85, v85
	v_mul_f32_e32 v91, v87, v87
	v_fmac_f32_e32 v90, v84, v84
	v_fmac_f32_e32 v91, v86, v86
	v_add_f32_e32 v90, v90, v91
	v_mul_f32_e32 v91, v81, v81
	v_fmac_f32_e32 v91, v80, v80
	v_add_f32_e32 v90, v90, v91
	v_mul_f32_e32 v91, v83, v83
	v_mul_f32_e32 v84, v24, v84
	v_mul_f32_e32 v85, v25, v85
	v_fmac_f32_e32 v91, v82, v82
	v_cvt_pk_bf16_f32 v84, v84, v85
	v_mul_f32_e32 v85, v26, v86
	v_mul_f32_e32 v86, v27, v87
	v_mul_f32_e32 v80, v28, v80
	v_mul_f32_e32 v81, v29, v81
	v_add_f32_e32 v90, v91, v90
	v_cvt_pk_bf16_f32 v85, v85, v86
	v_cvt_pk_bf16_f32 v86, v80, v81
	v_mul_f32_e32 v80, v30, v82
	v_mul_f32_e32 v81, v31, v83
	v_add_f32_e32 v90, v104, v90
	v_cvt_pk_bf16_f32 v87, v80, v81
	v_lshl_add_u64 v[80:81], v[172:173], 1, v[88:89]
	global_store_dwordx4 v[80:81], v[84:87], off offset:256
	ds_bpermute_b32 v80, v154, v90
	s_waitcnt lgkmcnt(0)
	v_add_f32_e32 v80, v90, v80
	ds_bpermute_b32 v81, v155, v80
	s_and_saveexec_b64 s[30:31], s[72:73]
	s_cbranch_execz .LBB0_1116
	v_lshlrev_b64 v[82:83], 6, v[96:97]
	v_lshl_add_u64 v[82:83], s[18:19], 0, v[82:83]
	v_lshl_add_u64 v[82:83], s[28:29], 2, v[82:83]
	s_lshl_b32 s96, s46, 2
	v_lshl_add_u64 v[82:83], v[82:83], 0, s[96:97]
	s_waitcnt lgkmcnt(0)
	v_add_f32_e32 v80, v80, v81
	global_store_dword v[82:83], v80, off

.LBB0_1126:
	v_lshl_add_u64 v[90:91], v[84:85], 0, v[174:175]
	v_lshl_add_u64 v[82:83], s[80:81], 0, v[86:87]
	global_load_dwordx4 v[204:207], v[90:91], off offset:528
	global_load_dwordx4 v[200:203], v[90:91], off offset:512
	global_load_dwordx4 v[86:89], v[90:91], off offset:16
	s_nop 0
	global_load_dwordx4 v[90:93], v[90:91], off
	v_ashrrev_i32_e32 v81, 31, v80
	s_waitcnt vmcnt(1)
	v_pk_fma_f32 v[72:73], v[72:73], v[56:57], v[86:87]
	s_waitcnt vmcnt(0)
	v_pk_fma_f32 v[78:79], v[78:79], v[54:55], v[92:93]
	v_pk_fma_f32 v[76:77], v[76:77], v[52:53], v[90:91]
	v_lshl_add_u64 v[86:87], v[82:83], 0, v[174:175]
	v_pk_fma_f32 v[74:75], v[74:75], v[58:59], v[88:89]
	global_store_dwordx4 v[86:87], v[76:79], off
	global_store_dwordx4 v[86:87], v[72:75], off offset:16
	v_mul_f32_e32 v86, v77, v77
	v_mul_f32_e32 v87, v79, v79
	v_fmac_f32_e32 v86, v76, v76
	v_fmac_f32_e32 v87, v78, v78
	v_add_f32_e32 v86, v86, v87
	v_mul_f32_e32 v87, v73, v73
	v_mul_f32_e32 v76, v48, v76
	v_mul_f32_e32 v77, v49, v77
	v_fmac_f32_e32 v87, v72, v72
	v_cvt_pk_bf16_f32 v76, v76, v77
	v_mul_f32_e32 v77, v50, v78
	v_mul_f32_e32 v78, v51, v79
	v_mul_f32_e32 v72, v60, v72
	v_mul_f32_e32 v73, v61, v73
	v_cvt_pk_bf16_f32 v77, v77, v78
	v_cvt_pk_bf16_f32 v78, v72, v73
	v_mul_f32_e32 v72, v62, v74
	v_mul_f32_e32 v73, v63, v75
	v_cvt_pk_bf16_f32 v79, v72, v73
	v_lshlrev_b64 v[72:73], 11, v[80:81]
	v_add_f32_e32 v86, v86, v87
	v_mul_f32_e32 v87, v75, v75
	v_lshl_add_u64 v[72:73], s[16:17], 0, v[72:73]
	v_fmac_f32_e32 v87, v74, v74
	v_lshl_add_u64 v[74:75], v[172:173], 1, v[72:73]
	global_store_dwordx4 v[74:75], v[76:79], off
	v_add_f32_e32 v88, v87, v86
	s_nop 0
	v_lshl_add_u64 v[78:79], v[84:85], 0, v[152:153]
	v_mov_b32_e32 v74, v204
	v_mov_b32_e32 v75, v205
	v_mov_b32_e32 v76, v206
	v_mov_b32_e32 v77, v207
	v_mov_b32_e32 v84, v200
	v_mov_b32_e32 v85, v201
	v_mov_b32_e32 v86, v202
	v_mov_b32_e32 v87, v203
	s_waitcnt vmcnt(3)
	v_pk_fma_f32 v[64:65], v[64:65], v[36:37], v[74:75]
	s_waitcnt vmcnt(3)
	v_pk_fma_f32 v[70:71], v[70:71], v[34:35], v[86:87]
	v_pk_fma_f32 v[68:69], v[68:69], v[32:33], v[84:85]
	v_lshl_add_u64 v[74:75], v[82:83], 0, v[152:153]
	v_pk_fma_f32 v[66:67], v[66:67], v[38:39], v[76:77]
	global_store_dwordx4 v[74:75], v[68:71], off offset:512
	global_store_dwordx4 v[74:75], v[64:67], off offset:528
	v_mul_f32_e32 v74, v69, v69
	v_mul_f32_e32 v75, v71, v71
	v_fmac_f32_e32 v74, v68, v68
	v_fmac_f32_e32 v75, v70, v70
	v_add_f32_e32 v74, v74, v75
	v_mul_f32_e32 v75, v65, v65
	v_fmac_f32_e32 v75, v64, v64
	v_add_f32_e32 v74, v74, v75
	v_mul_f32_e32 v75, v67, v67
	v_mul_f32_e32 v68, v24, v68
	v_mul_f32_e32 v69, v25, v69
	v_fmac_f32_e32 v75, v66, v66
	v_cvt_pk_bf16_f32 v68, v68, v69
	v_mul_f32_e32 v69, v26, v70
	v_mul_f32_e32 v70, v27, v71
	v_mul_f32_e32 v64, v28, v64
	v_mul_f32_e32 v65, v29, v65
	v_add_f32_e32 v74, v75, v74
	v_cvt_pk_bf16_f32 v69, v69, v70
	v_cvt_pk_bf16_f32 v70, v64, v65
	v_mul_f32_e32 v64, v30, v66
	v_mul_f32_e32 v65, v31, v67
	v_add_f32_e32 v74, v88, v74
	v_cvt_pk_bf16_f32 v71, v64, v65
	v_lshl_add_u64 v[64:65], v[172:173], 1, v[72:73]
	global_store_dwordx4 v[64:65], v[68:71], off offset:256
	ds_bpermute_b32 v64, v154, v74
	s_waitcnt lgkmcnt(0)
	v_add_f32_e32 v64, v74, v64
	ds_bpermute_b32 v65, v155, v64
	s_and_saveexec_b64 s[30:31], s[72:73]
	s_cbranch_execz .LBB0_1128
	v_lshlrev_b64 v[66:67], 6, v[80:81]
	v_lshl_add_u64 v[66:67], s[18:19], 0, v[66:67]
	v_lshl_add_u64 v[66:67], s[28:29], 2, v[66:67]
	s_lshl_b32 s96, s46, 2
	v_lshl_add_u64 v[66:67], v[66:67], 0, s[96:97]
	s_waitcnt lgkmcnt(0)
	v_add_f32_e32 v64, v64, v65
	global_store_dword v[66:67], v64, off

.LBB0_1138:
	v_lshl_add_u64 v[74:75], v[68:69], 0, v[174:175]
	v_lshl_add_u64 v[66:67], s[80:81], 0, v[70:71]
	global_load_dwordx4 v[204:207], v[74:75], off offset:528
	global_load_dwordx4 v[200:203], v[74:75], off offset:512
	global_load_dwordx4 v[70:73], v[74:75], off offset:16
	s_nop 0
	global_load_dwordx4 v[74:77], v[74:75], off
	v_ashrrev_i32_e32 v65, 31, v64
	s_waitcnt vmcnt(1)
	v_pk_fma_f32 v[40:41], v[40:41], v[56:57], v[70:71]
	s_waitcnt vmcnt(0)
	v_pk_fma_f32 v[46:47], v[46:47], v[54:55], v[76:77]
	v_pk_fma_f32 v[44:45], v[44:45], v[52:53], v[74:75]
	v_lshl_add_u64 v[70:71], v[66:67], 0, v[174:175]
	v_pk_fma_f32 v[42:43], v[42:43], v[58:59], v[72:73]
	global_store_dwordx4 v[70:71], v[44:47], off
	global_store_dwordx4 v[70:71], v[40:43], off offset:16
	v_mul_f32_e32 v70, v45, v45
	v_mul_f32_e32 v71, v47, v47
	v_fmac_f32_e32 v70, v44, v44
	v_fmac_f32_e32 v71, v46, v46
	v_add_f32_e32 v70, v70, v71
	v_mul_f32_e32 v71, v41, v41
	v_mul_f32_e32 v44, v48, v44
	v_mul_f32_e32 v45, v49, v45
	v_fmac_f32_e32 v71, v40, v40
	v_cvt_pk_bf16_f32 v44, v44, v45
	v_mul_f32_e32 v45, v50, v46
	v_mul_f32_e32 v46, v51, v47
	v_mul_f32_e32 v40, v60, v40
	v_mul_f32_e32 v41, v61, v41
	v_cvt_pk_bf16_f32 v45, v45, v46
	v_cvt_pk_bf16_f32 v46, v40, v41
	v_mul_f32_e32 v40, v62, v42
	v_mul_f32_e32 v41, v63, v43
	v_cvt_pk_bf16_f32 v47, v40, v41
	v_lshlrev_b64 v[40:41], 11, v[64:65]
	v_add_f32_e32 v70, v70, v71
	v_mul_f32_e32 v71, v43, v43
	v_lshl_add_u64 v[40:41], s[16:17], 0, v[40:41]
	v_fmac_f32_e32 v71, v42, v42
	v_lshl_add_u64 v[42:43], v[172:173], 1, v[40:41]
	global_store_dwordx4 v[42:43], v[44:47], off
	v_add_f32_e32 v72, v71, v70
	s_nop 0
	v_lshl_add_u64 v[46:47], v[68:69], 0, v[152:153]
	v_mov_b32_e32 v42, v204
	v_mov_b32_e32 v43, v205
	v_mov_b32_e32 v44, v206
	v_mov_b32_e32 v45, v207
	v_mov_b32_e32 v68, v200
	v_mov_b32_e32 v69, v201
	v_mov_b32_e32 v70, v202
	v_mov_b32_e32 v71, v203
	s_waitcnt vmcnt(3)
	v_pk_fma_f32 v[16:17], v[16:17], v[36:37], v[42:43]
	s_waitcnt vmcnt(3)
	v_pk_fma_f32 v[22:23], v[22:23], v[34:35], v[70:71]
	v_pk_fma_f32 v[20:21], v[20:21], v[32:33], v[68:69]
	v_lshl_add_u64 v[42:43], v[66:67], 0, v[152:153]
	v_pk_fma_f32 v[18:19], v[18:19], v[38:39], v[44:45]
	global_store_dwordx4 v[42:43], v[20:23], off offset:512
	global_store_dwordx4 v[42:43], v[16:19], off offset:528
	v_mul_f32_e32 v42, v21, v21
	v_mul_f32_e32 v43, v23, v23
	v_fmac_f32_e32 v42, v20, v20
	v_fmac_f32_e32 v43, v22, v22
	v_add_f32_e32 v42, v42, v43
	v_mul_f32_e32 v43, v17, v17
	v_fmac_f32_e32 v43, v16, v16
	v_add_f32_e32 v42, v42, v43
	v_mul_f32_e32 v43, v19, v19
	v_mul_f32_e32 v20, v24, v20
	v_mul_f32_e32 v21, v25, v21
	v_fmac_f32_e32 v43, v18, v18
	v_cvt_pk_bf16_f32 v20, v20, v21
	v_mul_f32_e32 v21, v26, v22
	v_mul_f32_e32 v22, v27, v23
	v_mul_f32_e32 v16, v28, v16
	v_mul_f32_e32 v17, v29, v17
	v_add_f32_e32 v42, v43, v42
	v_cvt_pk_bf16_f32 v21, v21, v22
	v_cvt_pk_bf16_f32 v22, v16, v17
	v_mul_f32_e32 v16, v30, v18
	v_mul_f32_e32 v17, v31, v19
	v_add_f32_e32 v42, v72, v42
	v_cvt_pk_bf16_f32 v23, v16, v17
	v_lshl_add_u64 v[16:17], v[172:173], 1, v[40:41]
	global_store_dwordx4 v[16:17], v[20:23], off offset:256
	ds_bpermute_b32 v16, v154, v42
	s_waitcnt lgkmcnt(0)
	v_add_f32_e32 v16, v42, v16
	ds_bpermute_b32 v17, v155, v16
	s_and_saveexec_b64 s[30:31], s[72:73]
	s_cbranch_execz .LBB0_1140
	v_lshlrev_b64 v[18:19], 6, v[64:65]
	v_lshl_add_u64 v[18:19], s[18:19], 0, v[18:19]
	v_lshl_add_u64 v[18:19], s[28:29], 2, v[18:19]
	s_lshl_b32 s96, s46, 2
	v_lshl_add_u64 v[18:19], v[18:19], 0, s[96:97]
	s_waitcnt lgkmcnt(0)
	v_add_f32_e32 v16, v16, v17
	global_store_dword v[18:19], v16, off

.LBB0_1150:
	v_lshl_add_u64 v[18:19], s[80:81], 0, v[22:23]
	v_lshl_add_u64 v[22:23], v[20:21], 0, v[174:175]
	global_load_dwordx4 v[204:207], v[22:23], off offset:528
	global_load_dwordx4 v[200:203], v[22:23], off offset:512
	global_load_dwordx4 v[40:43], v[22:23], off offset:16
	global_load_dwordx4 v[44:47], v[22:23], off
	v_lshl_add_u64 v[22:23], v[18:19], 0, v[174:175]
	v_ashrrev_i32_e32 v17, 31, v16
	s_waitcnt vmcnt(1)
	v_pk_fma_f32 v[10:11], v[10:11], v[58:59], v[42:43]
	s_waitcnt vmcnt(0)
	v_pk_fma_f32 v[14:15], v[14:15], v[54:55], v[46:47]
	v_pk_fma_f32 v[12:13], v[12:13], v[52:53], v[44:45]
	v_pk_fma_f32 v[8:9], v[8:9], v[56:57], v[40:41]
	global_store_dwordx4 v[22:23], v[12:15], off
	global_store_dwordx4 v[22:23], v[8:11], off offset:16
	v_mul_f32_e32 v22, v13, v13
	v_mul_f32_e32 v23, v15, v15
	v_fmac_f32_e32 v22, v12, v12
	v_fmac_f32_e32 v23, v14, v14
	v_add_f32_e32 v22, v22, v23
	v_mul_f32_e32 v23, v9, v9
	v_mul_f32_e32 v12, v48, v12
	v_mul_f32_e32 v13, v49, v13
	v_fmac_f32_e32 v23, v8, v8
	v_cvt_pk_bf16_f32 v12, v12, v13
	v_mul_f32_e32 v13, v50, v14
	v_mul_f32_e32 v14, v51, v15
	v_mul_f32_e32 v8, v60, v8
	v_mul_f32_e32 v9, v61, v9
	v_cvt_pk_bf16_f32 v13, v13, v14
	v_cvt_pk_bf16_f32 v14, v8, v9
	v_mul_f32_e32 v8, v62, v10
	v_mul_f32_e32 v9, v63, v11
	v_cvt_pk_bf16_f32 v15, v8, v9
	v_lshlrev_b64 v[8:9], 11, v[16:17]
	v_add_f32_e32 v22, v22, v23
	v_mul_f32_e32 v23, v11, v11
	v_lshl_add_u64 v[8:9], s[16:17], 0, v[8:9]
	v_fmac_f32_e32 v23, v10, v10
	v_lshl_add_u64 v[10:11], v[172:173], 1, v[8:9]
	global_store_dwordx4 v[10:11], v[12:15], off
	v_add_f32_e32 v40, v23, v22
	s_nop 0
	v_lshl_add_u64 v[14:15], v[20:21], 0, v[152:153]
	v_mov_b32_e32 v10, v204
	v_mov_b32_e32 v11, v205
	v_mov_b32_e32 v12, v206
	v_mov_b32_e32 v13, v207
	v_mov_b32_e32 v20, v200
	v_mov_b32_e32 v21, v201
	v_mov_b32_e32 v22, v202
	v_mov_b32_e32 v23, v203
	s_waitcnt vmcnt(3)
	v_pk_fma_f32 v[0:1], v[0:1], v[36:37], v[10:11]
	s_waitcnt vmcnt(3)
	v_pk_fma_f32 v[6:7], v[6:7], v[34:35], v[22:23]
	v_pk_fma_f32 v[4:5], v[4:5], v[32:33], v[20:21]
	v_lshl_add_u64 v[10:11], v[18:19], 0, v[152:153]
	v_pk_fma_f32 v[2:3], v[2:3], v[38:39], v[12:13]
	global_store_dwordx4 v[10:11], v[4:7], off offset:512
	global_store_dwordx4 v[10:11], v[0:3], off offset:528
	v_mul_f32_e32 v10, v5, v5
	v_mul_f32_e32 v11, v7, v7
	v_fmac_f32_e32 v10, v4, v4
	v_fmac_f32_e32 v11, v6, v6
	v_add_f32_e32 v10, v10, v11
	v_mul_f32_e32 v11, v1, v1
	v_fmac_f32_e32 v11, v0, v0
	v_add_f32_e32 v10, v10, v11
	v_mul_f32_e32 v11, v3, v3
	v_mul_f32_e32 v4, v24, v4
	v_mul_f32_e32 v5, v25, v5
	v_fmac_f32_e32 v11, v2, v2
	v_cvt_pk_bf16_f32 v4, v4, v5
	v_mul_f32_e32 v5, v26, v6
	v_mul_f32_e32 v6, v27, v7
	v_mul_f32_e32 v0, v28, v0
	v_mul_f32_e32 v1, v29, v1
	v_add_f32_e32 v10, v11, v10
	v_cvt_pk_bf16_f32 v5, v5, v6
	v_cvt_pk_bf16_f32 v6, v0, v1
	v_mul_f32_e32 v0, v30, v2
	v_mul_f32_e32 v1, v31, v3
	v_add_f32_e32 v10, v40, v10
	v_cvt_pk_bf16_f32 v7, v0, v1
	v_lshl_add_u64 v[0:1], v[172:173], 1, v[8:9]
	global_store_dwordx4 v[0:1], v[4:7], off offset:256
	ds_bpermute_b32 v0, v154, v10
	s_waitcnt lgkmcnt(0)
	v_add_f32_e32 v0, v10, v0
	ds_bpermute_b32 v1, v155, v0
	s_and_saveexec_b64 s[30:31], s[72:73]
	s_cbranch_execz .LBB0_1152
	v_lshlrev_b64 v[2:3], 6, v[16:17]
	v_lshl_add_u64 v[2:3], s[18:19], 0, v[2:3]
	v_lshl_add_u64 v[2:3], s[28:29], 2, v[2:3]
	s_lshl_b32 s96, s46, 2
	v_lshl_add_u64 v[2:3], v[2:3], 0, s[96:97]
	s_waitcnt lgkmcnt(0)
	v_add_f32_e32 v0, v0, v1
	global_store_dword v[2:3], v0, off
